# v9 plus phase-0 load balance: the small transpose jobs (ple_proj, pool_w) start at different waves instead of all at wave 0
# speedup vs baseline: 1.0088x; 1.0088x over previous
.LBB0_118:
	s_or_b64 exec, exec, s[50:51]
	s_lshl_b64 s[30:31], s[22:23], 20
	s_lshl_b32 s0, s22, 8
	s_addk_i32 s0, 0x400
	s_cmp_eq_u32 s80, 0x100
	s_cselect_b32 s0, s0, 0
	v_subrev_u32_e32 v40, s0, v10
	v_cmp_gt_u32_e32 vcc, 0x100, v40
	s_and_saveexec_b64 s[34:35], vcc
	s_cbranch_execz .LBB0_121
	s_load_dwordx2 s[0:1], s[28:29], 0xd8
	s_lshl_b64 s[18:19], s[22:23], 21
	v_lshl_add_u64 v[0:1], v[26:27], 0, s[30:31]
	v_lshlrev_b32_e32 v35, 5, v40
	s_mov_b64 s[50:51], 0
	s_waitcnt lgkmcnt(0)
	s_add_u32 s18, s0, s18
	s_addc_u32 s19, s1, s19
	s_lshl_b32 s0, s8, 5
	v_lshl_add_u64 v[2:3], s[18:19], 0, v[156:157]

.LBB0_123:
	s_lshl_b32 s1, s22, 2
	s_add_u32 s1, s1, s0
	s_lshl_b32 s1, s1, 5
	s_addk_i32 s1, 0x200
	s_cmp_eq_u32 s80, 0x100
	s_cselect_b32 s1, s1, 0
	v_subrev_u32_e32 v41, s1, v10
	v_cmp_gt_u32_e32 vcc, 32, v41
	s_and_saveexec_b64 s[34:35], vcc
	s_cbranch_execz .LBB0_122
	s_load_dwordx2 s[18:19], s[28:29], 0x48
	s_mov_b64 s[50:51], 0
	v_lshlrev_b32_e32 v40, 5, v41
	s_waitcnt lgkmcnt(0)
	s_add_u32 s1, s18, s30
	s_addc_u32 s9, s19, s31
	s_lshl_b32 s16, s0, 16
	s_lshl_b64 s[18:19], s[16:17], 2
	s_add_u32 s18, s1, s18
	s_addc_u32 s19, s9, s19
	s_lshl_b32 s1, s8, 5
	v_lshl_add_u64 v[2:3], s[18:19], 0, v[156:157]
